# GEMM2 restructure with P=80, pass C in reversed WG order
# speedup vs baseline: 1.0411x; 1.0130x over previous
; __global__ void __launch_bounds__(NWAVES * 64, 2) hybrid_fwd(Args A) {
;     ...
;             else if ((s == 2 && EN(3)) || (s == 3 && EN(4)) || (s == 4 && EN(5))) {
;                 const bool split = C.G >= 192; bool go = (s == 4); int k0 = split ? KSPLIT : 0, kl = D - k0, gg = C.G, cc = C.bid, mrows = M; size_t roff = 0;
;                 if (s == 2) { go = phase_mixers(A, C, l, rep ? DUP_UN : 7); k0 = 0; kl = KSPLIT; gg = C.G - 128; cc = C.bid - 128; mrows = MP; }
;                 if (s == 3) { phase_post(A, C, l, split ? 8 : 0); go = split && C.bid < 8 && !rep; k0 = 0; kl = KSPLIT; gg = 8; cc = C.bid; mrows = MS; roff = (size_t)MP * D; }
;                 if (go) { pg8::Gemm g{WS_PTR(const bf16, WS_XN) + roff + k0, WS_PTR(const bf16, WS_WOUTT) + (size_t)l * D * D + k0, mrows, D, kl, D}; pg8::StaticOrder S; S.init(mrows, D, gg, cc);
;                     const bool first = (l == 0) && (s != 4 || !split);
;                     float* Hout = ((rep && s == 4) ? WS_PTR(float, WS_U) : A.out) + roff;
;                     pg8::EpiResN E{Hout, first ? (s == 3 ? A.in[I_XS] : A.in[I_XP]) : Hout, first ? A.in[I_XS] - (size_t)MP * D : Hout, WS_PTR(bf16, WS_HB), WS_PTR(float, WS_SS) + (size_t)(l + 1) * M, s == 4 && !rep};
;                     pg8::gemm_phase<pg8::EpiResN, pg8::StaticOrder, G2_ALIGN, true>(C.lds, g, S, E); }
.LBB0_675:
	s_movk_i32 s11, 0x50
	s_mov_b32 s98, 0
	v_writelane_b32 v255, s98, 61
	v_writelane_b32 v255, s98, 62
	v_writelane_b32 v255, s98, 63
	v_readlane_b32 s30, v253, 0
	v_readlane_b32 s17, v253, 3
	v_readlane_b32 s3, v253, 19
	v_readlane_b32 s8, v253, 18
	s_branch .LBB0_1183

; __global__ void __launch_bounds__(NWAVES * 64, 2) hybrid_fwd(Args A) {
;     ...
;                 if (s == 2) { go = phase_mixers(A, C, l, rep ? DUP_UN : 7); k0 = 0; kl = KSPLIT; gg = C.G - 128; cc = C.bid - 128; mrows = MP; }
;                 if (s == 3) { phase_post(A, C, l, split ? 8 : 0); go = split && C.bid < 8 && !rep; k0 = 0; kl = KSPLIT; gg = 8; cc = C.bid; mrows = MS; roff = (size_t)MP * D; }
;                 if (go) { pg8::Gemm g{WS_PTR(const bf16, WS_XN) + roff + k0, WS_PTR(const bf16, WS_WOUTT) + (size_t)l * D * D + k0, mrows, D, kl, D}; pg8::StaticOrder S; S.init(mrows, D, gg, cc);
.LBB0_1181:
.LBB0_1182:
	s_mov_b32 s8, 0
	s_movk_i32 s3, 0x500
	s_movk_i32 s11, 0x50
	v_readlane_b32 s30, v253, 35
	v_readlane_b32 s17, v253, 34

; __global__ void __launch_bounds__(NWAVES * 64, 2) hybrid_fwd(Args A) {
;     ...
;             else if ((s == 2 && EN(3)) || (s == 3 && EN(4)) || (s == 4 && EN(5))) {
;                 const bool split = C.G >= 192; bool go = (s == 4); int k0 = split ? KSPLIT : 0, kl = D - k0, gg = C.G, cc = C.bid, mrows = M; size_t roff = 0;
;                 if (s == 2) { go = phase_mixers(A, C, l, rep ? DUP_UN : 7); k0 = 0; kl = KSPLIT; gg = C.G - 128; cc = C.bid - 128; mrows = MP; }
;                 if (s == 3) { phase_post(A, C, l, split ? 8 : 0); go = split && C.bid < 8 && !rep; k0 = 0; kl = KSPLIT; gg = 8; cc = C.bid; mrows = MS; roff = (size_t)MP * D; }
;                 if (go) { pg8::Gemm g{WS_PTR(const bf16, WS_XN) + roff + k0, WS_PTR(const bf16, WS_WOUTT) + (size_t)l * D * D + k0, mrows, D, kl, D}; pg8::StaticOrder S; S.init(mrows, D, gg, cc);
;                     const bool first = (l == 0) && (s != 4 || !split);
;                     float* Hout = ((rep && s == 4) ? WS_PTR(float, WS_U) : A.out) + roff;
;                     pg8::EpiResN E{Hout, first ? (s == 3 ? A.in[I_XS] : A.in[I_XP]) : Hout, first ? A.in[I_XS] - (size_t)MP * D : Hout, WS_PTR(bf16, WS_HB), WS_PTR(float, WS_SS) + (size_t)(l + 1) * M, s == 4 && !rep};
;                     pg8::gemm_phase<pg8::EpiResN, pg8::StaticOrder, G2_ALIGN, true>(C.lds, g, S, E); }
.Lmy_g2_passC:
	s_movk_i32 s11, 0x30
	s_mov_b64 s[40:41], 0x2800000
	v_readlane_b32 s17, v253, 3
	v_readlane_b32 s30, v253, 0
	s_nop 0
	s_sub_i32 s30, 0xff, s30
	s_movk_i32 s3, 0x800
	s_mov_b32 s8, 0
	s_mov_b32 s98, 0x5000
	v_writelane_b32 v255, s98, 63
	s_mov_b32 s98, 1
	v_writelane_b32 v255, s98, 62
	s_mov_b64 s[52:53], -1
	s_mov_b64 s[38:39], 0
	s_branch .LBB0_1189
